# even attention unit tail: 16 read-back loads + 16 sub_norm gain loads issued together with one wait instead of one vmcnt(0) per load (on top of v5)
# baseline (speedup 1.0000x reference)
; __global__ void __launch_bounds__(512, 2) mega_fwd(Params p_arg) {
;     ...
;           float ss = 0.f;
; #pragma unroll
;           for (int eb = 0; eb < 4; ++eb)
; #pragma unroll
;             for (int i4 = 0; i4 < 4; ++i4) {
;               const u32x2 w = *(const volatile u32x2*)(dst + 32 * eb + 8 * i4 + 4 * h);
;               const float a0 = __builtin_bit_cast(float, w.x << 16), a1 = __builtin_bit_cast(float, w.x & 0xffff0000u);
;               const float a2 = __builtin_bit_cast(float, w.y << 16), a3 = __builtin_bit_cast(float, w.y & 0xffff0000u);
;               o[eb][4 * i4] = a0 - lam * o[eb][4 * i4]; o[eb][4 * i4 + 1] = a1 - lam * o[eb][4 * i4 + 1];
;               o[eb][4 * i4 + 2] = a2 - lam * o[eb][4 * i4 + 2]; o[eb][4 * i4 + 3] = a3 - lam * o[eb][4 * i4 + 3];
;               ss += (o[eb][4 * i4] * o[eb][4 * i4] + o[eb][4 * i4 + 1] * o[eb][4 * i4 + 1]) + (o[eb][4 * i4 + 2] * o[eb][4 * i4 + 2] + o[eb][4 * i4 + 3] * o[eb][4 * i4 + 3]);
;             }
;     ...
;               for (int c = 0; c < 4; ++c) v[c] = o[eb][4 * i4 + c] * rn * p.ev_sub_norm[32 * eb + 8 * i4 + 4 * h + c];
.LBB0_574:
	s_load_dwordx2 s[4:5], s[24:25], 0x90
	global_load_dwordx2 v[70:71], v[210:211], off offset:1024 sc0 sc1
	global_load_dwordx2 v[68:69], v[210:211], off offset:1040 sc0 sc1
	global_load_dwordx2 v[66:67], v[210:211], off offset:1056 sc0 sc1
	global_load_dwordx2 v[64:65], v[210:211], off offset:1072 sc0 sc1
	global_load_dwordx2 v[72:73], v[210:211], off offset:1088 sc0 sc1
	global_load_dwordx2 v[74:75], v[210:211], off offset:1104 sc0 sc1
	global_load_dwordx2 v[76:77], v[210:211], off offset:1120 sc0 sc1
	global_load_dwordx2 v[78:79], v[210:211], off offset:1136 sc0 sc1
	global_load_dwordx2 v[82:83], v[210:211], off offset:1152 sc0 sc1
	global_load_dwordx2 v[90:91], v[210:211], off offset:1168 sc0 sc1
	global_load_dwordx2 v[92:93], v[210:211], off offset:1184 sc0 sc1
	global_load_dwordx2 v[94:95], v[210:211], off offset:1200 sc0 sc1
	global_load_dwordx2 v[96:97], v[210:211], off offset:1216 sc0 sc1
	global_load_dwordx2 v[98:99], v[210:211], off offset:1232 sc0 sc1
	global_load_dwordx2 v[176:177], v[210:211], off offset:1248 sc0 sc1
	global_load_dwordx2 v[178:179], v[210:211], off offset:1264 sc0 sc1
	s_waitcnt lgkmcnt(0)
	global_load_dwordx4 v[112:115], v222, s[4:5]
	global_load_dwordx4 v[116:119], v222, s[4:5] offset:32
	global_load_dwordx4 v[120:123], v222, s[4:5] offset:64
	global_load_dwordx4 v[124:127], v222, s[4:5] offset:96
	global_load_dwordx4 v[128:131], v222, s[4:5] offset:128
	global_load_dwordx4 v[132:135], v222, s[4:5] offset:160
	global_load_dwordx4 v[136:139], v222, s[4:5] offset:192
	global_load_dwordx4 v[140:143], v222, s[4:5] offset:224
	global_load_dwordx4 v[144:147], v222, s[4:5] offset:256
	global_load_dwordx4 v[148:151], v222, s[4:5] offset:288
	global_load_dwordx4 v[152:155], v222, s[4:5] offset:320
	global_load_dwordx4 v[156:159], v222, s[4:5] offset:352
	global_load_dwordx4 v[160:163], v222, s[4:5] offset:384
	global_load_dwordx4 v[164:167], v222, s[4:5] offset:416
	global_load_dwordx4 v[168:171], v222, s[4:5] offset:448
	global_load_dwordx4 v[172:175], v222, s[4:5] offset:480
	s_waitcnt vmcnt(16)
	v_mov_b32_e32 v80, v213
	s_nop 1
	v_permlane32_swap_b32_e32 v213, v80
	v_mov_b32_e32 v85, v50
	v_mov_b32_e32 v50, v53
	v_mov_b32_e32 v53, v55
	v_mov_b32_e32 v55, v58
	v_mov_b32_e32 v58, v61
	v_mov_b32_e32 v61, v63
	v_mov_b32_e32 v63, v34
	v_add_f32_e32 v34, v213, v80
	v_rcp_f32_e32 v80, v34
	v_mov_b32_e32 v84, v49
	v_mov_b32_e32 v49, v51
	v_mov_b32_e32 v51, v54
	v_mov_b32_e32 v54, v57
	v_mov_b32_e32 v57, v59
	v_mov_b32_e32 v59, v62
	v_mov_b32_e32 v62, v33
	v_mov_b32_e32 v33, v35
	v_pk_mul_f32 v[34:35], v[84:85], v[80:81] op_sel_hi:[1,0]
	v_pk_mul_f32 v[100:101], v[32:33], v[80:81] op_sel_hi:[1,0]
	v_pk_mul_f32 v[48:49], v[48:49], v[80:81] op_sel_hi:[1,0]
	v_pk_mul_f32 v[84:85], v[58:59], v[80:81] op_sel_hi:[1,0]
	v_pk_mul_f32 v[50:51], v[50:51], v[80:81] op_sel_hi:[1,0]
	v_pk_mul_f32 v[52:53], v[52:53], v[80:81] op_sel_hi:[1,0]
	v_pk_mul_f32 v[54:55], v[54:55], v[80:81] op_sel_hi:[1,0]
	v_pk_mul_f32 v[62:63], v[62:63], v[80:81] op_sel_hi:[1,0]
	v_pk_mul_f32 v[56:57], v[56:57], v[80:81] op_sel_hi:[1,0]
	v_pk_mul_f32 v[60:61], v[60:61], v[80:81] op_sel_hi:[1,0]
	s_add_i32 s36, s36, s28
	s_cmpk_gt_i32 s36, 0xff
	s_waitcnt lgkmcnt(0)
	v_and_b32_e32 v32, 0xffff0000, v72
	v_lshlrev_b32_e32 v33, 16, v73
	v_lshlrev_b32_e32 v58, 16, v72
	v_and_b32_e32 v59, 0xffff0000, v73
	v_and_b32_e32 v104, 0xffff0000, v78
	v_lshlrev_b32_e32 v105, 16, v79
	v_lshlrev_b32_e32 v106, 16, v78
	v_and_b32_e32 v107, 0xffff0000, v79
	v_pk_fma_f32 v[78:79], v[204:205], v[34:35], v[32:33] neg_lo:[1,0,0] neg_hi:[1,0,0]
	v_and_b32_e32 v88, 0xffff0000, v76
	v_lshlrev_b32_e32 v89, 16, v77
	v_lshlrev_b32_e32 v102, 16, v76
	v_and_b32_e32 v103, 0xffff0000, v77
	v_pk_fma_f32 v[76:77], v[204:205], v[48:49], v[58:59] neg_lo:[1,0,0] neg_hi:[1,0,0]
	v_pk_mul_f32 v[34:35], v[78:79], v[78:79]
	v_and_b32_e32 v72, 0xffff0000, v74
	v_lshlrev_b32_e32 v73, 16, v75
	v_lshlrev_b32_e32 v110, 16, v82
	v_and_b32_e32 v111, 0xffff0000, v83
	v_pk_fma_f32 v[34:35], v[76:77], v[76:77], v[34:35]
	v_lshlrev_b32_e32 v86, 16, v74
	v_and_b32_e32 v87, 0xffff0000, v75
	v_and_b32_e32 v108, 0xffff0000, v82
	v_lshlrev_b32_e32 v109, 16, v83
	v_pk_fma_f32 v[74:75], v[204:205], v[50:51], v[72:73] neg_lo:[1,0,0] neg_hi:[1,0,0]
	v_pk_add_f32 v[82:83], v[34:35], v[34:35] op_sel:[0,1] op_sel_hi:[1,0]
	v_pk_fma_f32 v[34:35], v[204:205], v[100:101], v[110:111] neg_lo:[1,0,0] neg_hi:[1,0,0]
	v_mov_b64_e32 v[100:101], v[176:177]
	v_pk_fma_f32 v[72:73], v[204:205], v[52:53], v[86:87] neg_lo:[1,0,0] neg_hi:[1,0,0]
	v_pk_mul_f32 v[52:53], v[74:75], v[74:75]
	v_pk_fma_f32 v[58:59], v[204:205], v[54:55], v[88:89] neg_lo:[1,0,0] neg_hi:[1,0,0]
	v_pk_fma_f32 v[32:33], v[204:205], v[62:63], v[108:109] neg_lo:[1,0,0] neg_hi:[1,0,0]
	v_pk_fma_f32 v[52:53], v[72:73], v[72:73], v[52:53]
	v_pk_fma_f32 v[56:57], v[204:205], v[56:57], v[102:103] neg_lo:[1,0,0] neg_hi:[1,0,0]
	v_pk_fma_f32 v[50:51], v[204:205], v[84:85], v[104:105] neg_lo:[1,0,0] neg_hi:[1,0,0]
	v_pk_mul_f32 v[54:55], v[58:59], v[58:59]
	v_pk_add_f32 v[84:85], v[52:53], v[52:53] op_sel:[0,1] op_sel_hi:[1,0]
	v_pk_mul_f32 v[52:53], v[32:33], v[32:33]
	v_pk_fma_f32 v[54:55], v[56:57], v[56:57], v[54:55]
	v_pk_fma_f32 v[52:53], v[34:35], v[34:35], v[52:53]
	v_pk_add_f32 v[86:87], v[54:55], v[54:55] op_sel:[0,1] op_sel_hi:[1,0]
	v_pk_add_f32 v[102:103], v[52:53], v[52:53] op_sel:[0,1] op_sel_hi:[1,0]
	v_mov_b32_e32 v52, v37
	v_mov_b32_e32 v53, v38
	v_mov_b32_e32 v37, v39
	v_and_b32_e32 v38, 0xffff0000, v90
	v_lshlrev_b32_e32 v39, 16, v91
	v_lshlrev_b32_e32 v54, 16, v90
	v_and_b32_e32 v55, 0xffff0000, v91
	v_mov_b64_e32 v[90:91], v[178:179]
; __global__ void __launch_bounds__(512, 2) mega_fwd(Params p_arg) {
;     ...
;             for (int i4 = 0; i4 < 4; ++i4) {
;               const u32x2 w = *(const volatile u32x2*)(dst + 32 * eb + 8 * i4 + 4 * h);
;               const float a0 = __builtin_bit_cast(float, w.x << 16), a1 = __builtin_bit_cast(float, w.x & 0xffff0000u);
;               const float a2 = __builtin_bit_cast(float, w.y << 16), a3 = __builtin_bit_cast(float, w.y & 0xffff0000u);
;               o[eb][4 * i4] = a0 - lam * o[eb][4 * i4]; o[eb][4 * i4 + 1] = a1 - lam * o[eb][4 * i4 + 1];
;               o[eb][4 * i4 + 2] = a2 - lam * o[eb][4 * i4 + 2]; o[eb][4 * i4 + 3] = a3 - lam * o[eb][4 * i4 + 3];
;               ss += (o[eb][4 * i4] * o[eb][4 * i4] + o[eb][4 * i4 + 1] * o[eb][4 * i4 + 1]) + (o[eb][4 * i4 + 2] * o[eb][4 * i4 + 2] + o[eb][4 * i4 + 3] * o[eb][4 * i4 + 3]);
;             }
	v_pk_mul_f32 v[52:53], v[52:53], v[80:81] op_sel_hi:[1,0]
	v_pk_mul_f32 v[36:37], v[36:37], v[80:81] op_sel_hi:[1,0]
	v_pk_fma_f32 v[52:53], v[204:205], v[52:53], v[38:39] neg_lo:[1,0,0] neg_hi:[1,0,0]
	v_pk_fma_f32 v[62:63], v[204:205], v[36:37], v[54:55] neg_lo:[1,0,0] neg_hi:[1,0,0]
	v_pk_mul_f32 v[36:37], v[52:53], v[52:53]
	v_pk_fma_f32 v[48:49], v[204:205], v[60:61], v[106:107] neg_lo:[1,0,0] neg_hi:[1,0,0]
	v_pk_fma_f32 v[36:37], v[62:63], v[62:63], v[36:37]
	v_pk_mul_f32 v[60:61], v[50:51], v[50:51]
	v_pk_add_f32 v[104:105], v[36:37], v[36:37] op_sel:[0,1] op_sel_hi:[1,0]
	v_mov_b32_e32 v36, v41
	v_mov_b32_e32 v37, v42
	v_mov_b32_e32 v41, v43
	v_pk_fma_f32 v[60:61], v[48:49], v[48:49], v[60:61]
	v_pk_mul_f32 v[36:37], v[36:37], v[80:81] op_sel_hi:[1,0]
	v_pk_mul_f32 v[38:39], v[40:41], v[80:81] op_sel_hi:[1,0]
	v_and_b32_e32 v40, 0xffff0000, v92
	v_lshlrev_b32_e32 v41, 16, v93
	v_pk_add_f32 v[88:89], v[60:61], v[60:61] op_sel:[0,1] op_sel_hi:[1,0]
	v_lshlrev_b32_e32 v42, 16, v92
	v_and_b32_e32 v43, 0xffff0000, v93
	v_pk_fma_f32 v[60:61], v[204:205], v[36:37], v[40:41] neg_lo:[1,0,0] neg_hi:[1,0,0]
	v_pk_fma_f32 v[54:55], v[204:205], v[38:39], v[42:43] neg_lo:[1,0,0] neg_hi:[1,0,0]
	v_pk_mul_f32 v[36:37], v[60:61], v[60:61]
	v_and_b32_e32 v40, 0xffff0000, v94
	v_pk_fma_f32 v[36:37], v[54:55], v[54:55], v[36:37]
	v_lshlrev_b32_e32 v41, 16, v95
	v_pk_add_f32 v[92:93], v[36:37], v[36:37] op_sel:[0,1] op_sel_hi:[1,0]
	v_mov_b32_e32 v36, v45
	v_mov_b32_e32 v37, v46
	v_pk_mul_f32 v[36:37], v[36:37], v[80:81] op_sel_hi:[1,0]
	v_mov_b32_e32 v45, v47
	v_pk_mul_f32 v[38:39], v[44:45], v[80:81] op_sel_hi:[1,0]
	v_lshlrev_b32_e32 v42, 16, v94
	v_and_b32_e32 v43, 0xffff0000, v95
	v_pk_fma_f32 v[46:47], v[204:205], v[36:37], v[40:41] neg_lo:[1,0,0] neg_hi:[1,0,0]
	v_pk_fma_f32 v[44:45], v[204:205], v[38:39], v[42:43] neg_lo:[1,0,0] neg_hi:[1,0,0]
	v_pk_mul_f32 v[36:37], v[46:47], v[46:47]
	v_lshlrev_b32_e32 v38, 16, v96
	v_pk_fma_f32 v[36:37], v[44:45], v[44:45], v[36:37]
	v_and_b32_e32 v39, 0xffff0000, v97
	v_pk_add_f32 v[94:95], v[36:37], v[36:37] op_sel:[0,1] op_sel_hi:[1,0]
	v_mov_b32_e32 v36, v17
	v_mov_b32_e32 v37, v18
	v_pk_mul_f32 v[36:37], v[36:37], v[80:81] op_sel_hi:[1,0]
	v_mov_b32_e32 v17, v19
	v_and_b32_e32 v18, 0xffff0000, v96
	v_lshlrev_b32_e32 v19, 16, v97
	v_pk_mul_f32 v[16:17], v[16:17], v[80:81] op_sel_hi:[1,0]
	v_pk_fma_f32 v[42:43], v[204:205], v[36:37], v[18:19] neg_lo:[1,0,0] neg_hi:[1,0,0]
	v_pk_fma_f32 v[40:41], v[204:205], v[16:17], v[38:39] neg_lo:[1,0,0] neg_hi:[1,0,0]
	v_pk_mul_f32 v[16:17], v[42:43], v[42:43]
	v_pk_fma_f32 v[16:17], v[40:41], v[40:41], v[16:17]
	s_nop 0
	v_pk_add_f32 v[96:97], v[16:17], v[16:17] op_sel:[0,1] op_sel_hi:[1,0]
	v_mov_b32_e32 v16, v21
	v_mov_b32_e32 v17, v22
	v_mov_b32_e32 v21, v23
	v_pk_mul_f32 v[16:17], v[16:17], v[80:81] op_sel_hi:[1,0]
	v_pk_mul_f32 v[18:19], v[20:21], v[80:81] op_sel_hi:[1,0]
	v_and_b32_e32 v20, 0xffff0000, v98
	v_lshlrev_b32_e32 v21, 16, v99
	v_lshlrev_b32_e32 v22, 16, v98
	v_and_b32_e32 v23, 0xffff0000, v99
	v_pk_fma_f32 v[38:39], v[204:205], v[16:17], v[20:21] neg_lo:[1,0,0] neg_hi:[1,0,0]
	v_pk_fma_f32 v[36:37], v[204:205], v[18:19], v[22:23] neg_lo:[1,0,0] neg_hi:[1,0,0]
	v_pk_mul_f32 v[16:17], v[38:39], v[38:39]
	s_waitcnt lgkmcnt(0)
	v_and_b32_e32 v20, 0xffff0000, v100
	v_pk_fma_f32 v[16:17], v[36:37], v[36:37], v[16:17]
	v_lshlrev_b32_e32 v21, 16, v101
	v_pk_add_f32 v[98:99], v[16:17], v[16:17] op_sel:[0,1] op_sel_hi:[1,0]
	v_mov_b32_e32 v16, v25
	v_mov_b32_e32 v17, v26
	v_pk_mul_f32 v[16:17], v[16:17], v[80:81] op_sel_hi:[1,0]
	v_mov_b32_e32 v25, v27
	v_pk_mul_f32 v[18:19], v[24:25], v[80:81] op_sel_hi:[1,0]
	v_lshlrev_b32_e32 v24, 16, v100
	v_and_b32_e32 v25, 0xffff0000, v101
	v_pk_fma_f32 v[22:23], v[204:205], v[16:17], v[20:21] neg_lo:[1,0,0] neg_hi:[1,0,0]
	v_pk_fma_f32 v[20:21], v[204:205], v[18:19], v[24:25] neg_lo:[1,0,0] neg_hi:[1,0,0]
	v_pk_mul_f32 v[16:17], v[22:23], v[22:23]
	v_and_b32_e32 v18, 0xffff0000, v90
	v_pk_fma_f32 v[16:17], v[20:21], v[20:21], v[16:17]
	v_lshlrev_b32_e32 v19, 16, v91
	v_pk_add_f32 v[100:101], v[16:17], v[16:17] op_sel:[0,1] op_sel_hi:[1,0]
	v_mov_b32_e32 v16, v29
	v_mov_b32_e32 v17, v30
	v_pk_mul_f32 v[16:17], v[16:17], v[80:81] op_sel_hi:[1,0]
	v_mov_b32_e32 v29, v31
	v_pk_mul_f32 v[24:25], v[28:29], v[80:81] op_sel_hi:[1,0]
	v_lshlrev_b32_e32 v26, 16, v90
	v_and_b32_e32 v27, 0xffff0000, v91
	v_pk_fma_f32 v[18:19], v[204:205], v[16:17], v[18:19] neg_lo:[1,0,0] neg_hi:[1,0,0]
	v_pk_fma_f32 v[16:17], v[204:205], v[24:25], v[26:27] neg_lo:[1,0,0] neg_hi:[1,0,0]
	v_pk_mul_f32 v[24:25], v[18:19], v[18:19]
	v_lshlrev_b32_e32 v90, 16, v70
	v_pk_fma_f32 v[28:29], v[16:17], v[16:17], v[24:25]
	v_and_b32_e32 v25, 64, v224
	v_xor_b32_e32 v24, 32, v224
	v_add_u32_e32 v25, 64, v25
	v_cmp_lt_i32_e32 vcc, v24, v25
	v_and_b32_e32 v25, 0xffff0000, v71
	v_and_b32_e32 v91, 0xffff0000, v70
	v_cndmask_b32_e32 v24, v224, v24, vcc
	v_lshlrev_b32_e32 v81, 2, v24
	v_pk_mul_f32 v[2:3], v[2:3], v[80:81] op_sel_hi:[1,0]
	v_lshlrev_b32_e32 v24, 16, v71
	v_pk_fma_f32 v[2:3], v[204:205], v[2:3], v[24:25] neg_lo:[1,0,0] neg_hi:[1,0,0]
	v_pk_mul_f32 v[0:1], v[0:1], v[80:81] op_sel_hi:[1,0]
	v_mul_f32_e32 v24, v3, v3
	v_pk_fma_f32 v[30:31], v[2:3], v[2:3], v[24:25] op_sel_hi:[1,1,0]
	s_waitcnt vmcnt(0)
; __global__ void __launch_bounds__(512, 2) mega_fwd(Params p_arg) {
;     ...
;             for (int i4 = 0; i4 < 4; ++i4) {
;               const u32x2 w = *(const volatile u32x2*)(dst + 32 * eb + 8 * i4 + 4 * h);
;               const float a0 = __builtin_bit_cast(float, w.x << 16), a1 = __builtin_bit_cast(float, w.x & 0xffff0000u);
;               const float a2 = __builtin_bit_cast(float, w.y << 16), a3 = __builtin_bit_cast(float, w.y & 0xffff0000u);
;               o[eb][4 * i4] = a0 - lam * o[eb][4 * i4]; o[eb][4 * i4 + 1] = a1 - lam * o[eb][4 * i4 + 1];
;               o[eb][4 * i4 + 2] = a2 - lam * o[eb][4 * i4 + 2]; o[eb][4 * i4 + 3] = a3 - lam * o[eb][4 * i4 + 3];
;               ss += (o[eb][4 * i4] * o[eb][4 * i4] + o[eb][4 * i4 + 1] * o[eb][4 * i4 + 1]) + (o[eb][4 * i4 + 2] * o[eb][4 * i4 + 2] + o[eb][4 * i4 + 3] * o[eb][4 * i4 + 3]);
;             }
;           ss += __shfl_xor(ss, 32);
	v_mov_b64_e32 v[24:25], v[112:113]
	v_mov_b64_e32 v[26:27], v[114:115]
	v_pk_fma_f32 v[70:71], v[204:205], v[0:1], v[90:91] neg_lo:[1,0,0] neg_hi:[1,0,0]
	v_pk_mul_f32 v[6:7], v[6:7], v[80:81] op_sel_hi:[1,0]
	v_mul_f32_e32 v0, v71, v71
	v_pk_fma_f32 v[0:1], v[70:71], v[70:71], v[0:1] op_sel_hi:[1,1,0]
	v_pk_mul_f32 v[4:5], v[4:5], v[80:81] op_sel_hi:[1,0]
	v_pk_add_f32 v[0:1], v[0:1], v[30:31]
	v_lshlrev_b32_e32 v30, 16, v69
	v_and_b32_e32 v31, 0xffff0000, v69
	v_lshlrev_b32_e32 v90, 16, v68
	v_and_b32_e32 v91, 0xffff0000, v68
	v_pk_fma_f32 v[6:7], v[204:205], v[6:7], v[30:31] neg_lo:[1,0,0] neg_hi:[1,0,0]
	v_pk_fma_f32 v[68:69], v[204:205], v[4:5], v[90:91] neg_lo:[1,0,0] neg_hi:[1,0,0]
	v_mul_f32_e32 v30, v7, v7
	v_mul_f32_e32 v4, v69, v69
	v_pk_fma_f32 v[30:31], v[6:7], v[6:7], v[30:31] op_sel_hi:[1,1,0]
	v_pk_fma_f32 v[4:5], v[68:69], v[68:69], v[4:5] op_sel_hi:[1,1,0]
	v_pk_mul_f32 v[8:9], v[8:9], v[80:81] op_sel_hi:[1,0]
	v_pk_add_f32 v[4:5], v[4:5], v[30:31]
	v_lshlrev_b32_e32 v30, 16, v66
	v_pk_add_f32 v[0:1], v[0:1], v[4:5]
	v_pk_mul_f32 v[4:5], v[10:11], v[80:81] op_sel_hi:[1,0]
	v_lshlrev_b32_e32 v10, 16, v67
	v_and_b32_e32 v11, 0xffff0000, v67
	v_and_b32_e32 v31, 0xffff0000, v66
	v_pk_fma_f32 v[10:11], v[204:205], v[4:5], v[10:11] neg_lo:[1,0,0] neg_hi:[1,0,0]
	v_pk_fma_f32 v[8:9], v[204:205], v[8:9], v[30:31] neg_lo:[1,0,0] neg_hi:[1,0,0]
	v_mul_f32_e32 v4, v11, v11
	v_mul_f32_e32 v30, v9, v9
	v_pk_fma_f32 v[4:5], v[10:11], v[10:11], v[4:5] op_sel_hi:[1,1,0]
	v_pk_fma_f32 v[30:31], v[8:9], v[8:9], v[30:31] op_sel_hi:[1,1,0]
	v_pk_mul_f32 v[12:13], v[12:13], v[80:81] op_sel_hi:[1,0]
	v_pk_add_f32 v[4:5], v[30:31], v[4:5]
	v_lshlrev_b32_e32 v30, 16, v64
	v_pk_add_f32 v[0:1], v[0:1], v[4:5]
	v_pk_mul_f32 v[4:5], v[14:15], v[80:81] op_sel_hi:[1,0]
	v_lshlrev_b32_e32 v14, 16, v65
	v_and_b32_e32 v15, 0xffff0000, v65
	v_and_b32_e32 v31, 0xffff0000, v64
	v_pk_fma_f32 v[14:15], v[204:205], v[4:5], v[14:15] neg_lo:[1,0,0] neg_hi:[1,0,0]
	v_pk_fma_f32 v[12:13], v[204:205], v[12:13], v[30:31] neg_lo:[1,0,0] neg_hi:[1,0,0]
	v_mul_f32_e32 v4, v15, v15
	v_mul_f32_e32 v30, v13, v13
	v_pk_fma_f32 v[4:5], v[14:15], v[14:15], v[4:5] op_sel_hi:[1,1,0]
	v_pk_fma_f32 v[30:31], v[12:13], v[12:13], v[30:31] op_sel_hi:[1,1,0]
	v_mov_b32_e32 v101, v29
	v_pk_add_f32 v[4:5], v[30:31], v[4:5]
	s_nop 0
	v_pk_add_f32 v[0:1], v[0:1], v[4:5]
	s_nop 0
	v_pk_add_f32 v[0:1], v[0:1], v[82:83]
	s_nop 0
	v_pk_add_f32 v[0:1], v[0:1], v[84:85]
	s_nop 0
	v_pk_add_f32 v[0:1], v[0:1], v[86:87]
	s_nop 0
	v_pk_add_f32 v[0:1], v[0:1], v[88:89]
	s_nop 0
	v_pk_add_f32 v[0:1], v[0:1], v[102:103]
	s_nop 0
	v_pk_add_f32 v[0:1], v[0:1], v[104:105]
	s_nop 0
	v_pk_add_f32 v[0:1], v[0:1], v[92:93]
	s_nop 0
	v_pk_add_f32 v[0:1], v[0:1], v[94:95]
	s_nop 0
	v_pk_add_f32 v[0:1], v[0:1], v[96:97]
	s_nop 0
	v_pk_add_f32 v[0:1], v[0:1], v[98:99]
	s_nop 0
	v_mov_b32_e32 v1, v28
	v_pk_add_f32 v[0:1], v[0:1], v[100:101]
	s_nop 0
	v_add_f32_e32 v0, v0, v1
	ds_bpermute_b32 v1, v81, v0
	s_waitcnt lgkmcnt(0)
; __device__ __forceinline__ unsigned pk2(float lo, float hi) { f32x2_t v = {lo, hi}; bf16x2_t b = __builtin_convertvector(v, bf16x2_t); return __builtin_bit_cast(unsigned, b); }
; __global__ void __launch_bounds__(512, 2) mega_fwd(Params p_arg) {
;     ...
;           ss += __shfl_xor(ss, 32);
;           const float rn = rsqrtf(ss * (1.f / 128.f) + EPS) * (1.f - lam_init);
; #pragma unroll
;           for (int eb = 0; eb < 4; ++eb)
; #pragma unroll
;             for (int i4 = 0; i4 < 4; ++i4) {
;               float v[4];
; #pragma unroll
;               for (int c = 0; c < 4; ++c) v[c] = o[eb][4 * i4 + c] * rn * p.ev_sub_norm[32 * eb + 8 * i4 + 4 * h + c];
;               u32x2 w; w.x = pk2(v[0], v[1]); w.y = pk2(v[2], v[3]);
;               *(u32x2*)(dst + 32 * eb + 8 * i4 + 4 * h) = w;
;             }
	v_add_f32_e32 v0, v0, v1
	v_fmamk_f32 v0, v0, 0x3c000000, v223
	v_mul_f32_e32 v1, 0x4b800000, v0
	v_cmp_gt_f32_e32 vcc, s33, v0
	s_nop 1
	v_cndmask_b32_e32 v0, v0, v1, vcc
	v_rsq_f32_e32 v0, v0
	s_nop 0
	v_mul_f32_e32 v1, 0x45800000, v0
	v_cndmask_b32_e32 v0, v0, v1, vcc
	v_mul_f32_e32 v0, 0x3f4ccccd, v0
	v_pk_mul_f32 v[4:5], v[70:71], v[0:1] op_sel_hi:[1,0]
	v_pk_mul_f32 v[2:3], v[2:3], v[0:1] op_sel_hi:[1,0]
	v_pk_mul_f32 v[4:5], v[24:25], v[4:5]
	v_pk_mul_f32 v[2:3], v[26:27], v[2:3]
	v_cvt_pk_bf16_f32 v4, v4, v5
	v_cvt_pk_bf16_f32 v5, v2, v3
	global_store_dwordx2 v[210:211], v[4:5], off offset:1024
	v_mov_b64_e32 v[2:3], v[116:117]
	v_mov_b64_e32 v[4:5], v[118:119]
	v_pk_mul_f32 v[24:25], v[68:69], v[0:1] op_sel_hi:[1,0]
	v_pk_mul_f32 v[6:7], v[6:7], v[0:1] op_sel_hi:[1,0]
	v_pk_mul_f32 v[2:3], v[2:3], v[24:25]
	v_pk_mul_f32 v[4:5], v[4:5], v[6:7]
	v_cvt_pk_bf16_f32 v2, v2, v3
	v_cvt_pk_bf16_f32 v3, v4, v5
	global_store_dwordx2 v[210:211], v[2:3], off offset:1040
	v_mov_b64_e32 v[2:3], v[120:121]
	v_mov_b64_e32 v[4:5], v[122:123]
	v_pk_mul_f32 v[6:7], v[8:9], v[0:1] op_sel_hi:[1,0]
	v_pk_mul_f32 v[8:9], v[14:15], v[0:1] op_sel_hi:[1,0]
	v_pk_mul_f32 v[2:3], v[2:3], v[6:7]
	v_pk_mul_f32 v[6:7], v[10:11], v[0:1] op_sel_hi:[1,0]
	v_cvt_pk_bf16_f32 v2, v2, v3
	v_pk_mul_f32 v[4:5], v[4:5], v[6:7]
	v_pk_mul_f32 v[6:7], v[12:13], v[0:1] op_sel_hi:[1,0]
	v_cvt_pk_bf16_f32 v3, v4, v5
	global_store_dwordx2 v[210:211], v[2:3], off offset:1056
	v_mov_b64_e32 v[2:3], v[124:125]
	v_mov_b64_e32 v[4:5], v[126:127]
	v_pk_mul_f32 v[2:3], v[6:7], v[2:3]
	v_pk_mul_f32 v[4:5], v[8:9], v[4:5]
	v_cvt_pk_bf16_f32 v2, v2, v3
	v_cvt_pk_bf16_f32 v3, v4, v5
	global_store_dwordx2 v[210:211], v[2:3], off offset:1072
	v_mov_b64_e32 v[2:3], v[128:129]
	v_mov_b64_e32 v[4:5], v[130:131]
	v_mov_b32_e32 v6, v76
	v_mov_b32_e32 v7, v78
	v_mov_b32_e32 v76, v79
	v_pk_mul_f32 v[6:7], v[6:7], v[0:1] op_sel_hi:[1,0]
	v_pk_mul_f32 v[8:9], v[76:77], v[0:1] op_sel_hi:[1,0]
	v_pk_mul_f32 v[2:3], v[6:7], v[2:3]
	v_pk_mul_f32 v[4:5], v[8:9], v[4:5]
	v_cvt_pk_bf16_f32 v2, v2, v3
	v_cvt_pk_bf16_f32 v3, v4, v5
	global_store_dwordx2 v[210:211], v[2:3], off offset:1088
	v_mov_b64_e32 v[2:3], v[132:133]
	v_mov_b64_e32 v[4:5], v[134:135]
	v_mov_b32_e32 v6, v72
	v_mov_b32_e32 v7, v74
	v_mov_b32_e32 v72, v75
	v_pk_mul_f32 v[6:7], v[6:7], v[0:1] op_sel_hi:[1,0]
	v_pk_mul_f32 v[8:9], v[72:73], v[0:1] op_sel_hi:[1,0]
	v_pk_mul_f32 v[2:3], v[6:7], v[2:3]
	v_pk_mul_f32 v[4:5], v[8:9], v[4:5]
	v_cvt_pk_bf16_f32 v2, v2, v3
	v_cvt_pk_bf16_f32 v3, v4, v5
	global_store_dwordx2 v[210:211], v[2:3], off offset:1104
	v_mov_b64_e32 v[2:3], v[136:137]
	v_mov_b64_e32 v[4:5], v[138:139]
	v_mov_b32_e32 v6, v56
	v_mov_b32_e32 v7, v58
	v_mov_b32_e32 v56, v59
	v_pk_mul_f32 v[6:7], v[6:7], v[0:1] op_sel_hi:[1,0]
	v_pk_mul_f32 v[8:9], v[56:57], v[0:1] op_sel_hi:[1,0]
	v_pk_mul_f32 v[2:3], v[6:7], v[2:3]
	v_pk_mul_f32 v[4:5], v[8:9], v[4:5]
	v_cvt_pk_bf16_f32 v2, v2, v3
	v_cvt_pk_bf16_f32 v3, v4, v5
	global_store_dwordx2 v[210:211], v[2:3], off offset:1120
	v_mov_b64_e32 v[2:3], v[140:141]
	v_mov_b64_e32 v[4:5], v[142:143]
	v_mov_b32_e32 v6, v48
	v_mov_b32_e32 v7, v50
	v_mov_b32_e32 v48, v51
	v_pk_mul_f32 v[6:7], v[6:7], v[0:1] op_sel_hi:[1,0]
	v_pk_mul_f32 v[8:9], v[48:49], v[0:1] op_sel_hi:[1,0]
	v_pk_mul_f32 v[2:3], v[6:7], v[2:3]
	v_pk_mul_f32 v[4:5], v[8:9], v[4:5]
	v_cvt_pk_bf16_f32 v2, v2, v3
	v_cvt_pk_bf16_f32 v3, v4, v5
	global_store_dwordx2 v[210:211], v[2:3], off offset:1136
	v_mov_b64_e32 v[2:3], v[144:145]
	v_mov_b64_e32 v[4:5], v[146:147]
	v_mov_b32_e32 v6, v34
	v_mov_b32_e32 v7, v32
	v_mov_b32_e32 v34, v33
	v_pk_mul_f32 v[6:7], v[6:7], v[0:1] op_sel_hi:[1,0]
	v_pk_mul_f32 v[8:9], v[34:35], v[0:1] op_sel_hi:[1,0]
	v_pk_mul_f32 v[2:3], v[6:7], v[2:3]
	v_pk_mul_f32 v[4:5], v[8:9], v[4:5]
	v_cvt_pk_bf16_f32 v2, v2, v3
	v_cvt_pk_bf16_f32 v3, v4, v5
	global_store_dwordx2 v[210:211], v[2:3], off offset:1152
	v_mov_b64_e32 v[2:3], v[148:149]
	v_mov_b64_e32 v[4:5], v[150:151]
	v_mov_b32_e32 v6, v62
	v_mov_b32_e32 v7, v52
	v_mov_b32_e32 v62, v53
	v_pk_mul_f32 v[6:7], v[6:7], v[0:1] op_sel_hi:[1,0]
	v_pk_mul_f32 v[8:9], v[62:63], v[0:1] op_sel_hi:[1,0]
	v_pk_mul_f32 v[2:3], v[6:7], v[2:3]
	v_pk_mul_f32 v[4:5], v[8:9], v[4:5]
	v_cvt_pk_bf16_f32 v2, v2, v3
	v_cvt_pk_bf16_f32 v3, v4, v5
	global_store_dwordx2 v[210:211], v[2:3], off offset:1168
	v_mov_b64_e32 v[2:3], v[152:153]
	v_mov_b64_e32 v[4:5], v[154:155]
	v_mov_b32_e32 v6, v54
	v_mov_b32_e32 v7, v60
	v_mov_b32_e32 v54, v61
	v_pk_mul_f32 v[6:7], v[6:7], v[0:1] op_sel_hi:[1,0]
	v_pk_mul_f32 v[8:9], v[54:55], v[0:1] op_sel_hi:[1,0]
	v_pk_mul_f32 v[2:3], v[6:7], v[2:3]
	v_pk_mul_f32 v[4:5], v[8:9], v[4:5]
	v_cvt_pk_bf16_f32 v2, v2, v3
	v_cvt_pk_bf16_f32 v3, v4, v5
	global_store_dwordx2 v[210:211], v[2:3], off offset:1184
	v_mov_b64_e32 v[2:3], v[156:157]
	v_mov_b64_e32 v[4:5], v[158:159]
	v_mov_b32_e32 v6, v44
	v_mov_b32_e32 v7, v46
	v_mov_b32_e32 v44, v47
	v_pk_mul_f32 v[6:7], v[6:7], v[0:1] op_sel_hi:[1,0]
	v_pk_mul_f32 v[8:9], v[44:45], v[0:1] op_sel_hi:[1,0]
	v_pk_mul_f32 v[2:3], v[6:7], v[2:3]
	v_pk_mul_f32 v[4:5], v[8:9], v[4:5]
	v_cvt_pk_bf16_f32 v2, v2, v3
	v_cvt_pk_bf16_f32 v3, v4, v5
	global_store_dwordx2 v[210:211], v[2:3], off offset:1200
	v_mov_b64_e32 v[2:3], v[160:161]
	v_mov_b64_e32 v[4:5], v[162:163]
	v_mov_b32_e32 v6, v40
	v_mov_b32_e32 v7, v42
	v_mov_b32_e32 v40, v43
	v_pk_mul_f32 v[6:7], v[6:7], v[0:1] op_sel_hi:[1,0]
	v_pk_mul_f32 v[8:9], v[40:41], v[0:1] op_sel_hi:[1,0]
	v_pk_mul_f32 v[2:3], v[6:7], v[2:3]
	v_pk_mul_f32 v[4:5], v[8:9], v[4:5]
	v_cvt_pk_bf16_f32 v2, v2, v3
	v_cvt_pk_bf16_f32 v3, v4, v5
	global_store_dwordx2 v[210:211], v[2:3], off offset:1216
	v_mov_b64_e32 v[2:3], v[164:165]
	v_mov_b64_e32 v[4:5], v[166:167]
	v_mov_b32_e32 v6, v36
	v_mov_b32_e32 v7, v38
	v_mov_b32_e32 v36, v39
	v_pk_mul_f32 v[6:7], v[6:7], v[0:1] op_sel_hi:[1,0]
	v_pk_mul_f32 v[8:9], v[36:37], v[0:1] op_sel_hi:[1,0]
	v_pk_mul_f32 v[2:3], v[6:7], v[2:3]
	v_pk_mul_f32 v[4:5], v[8:9], v[4:5]
	v_cvt_pk_bf16_f32 v2, v2, v3
	v_cvt_pk_bf16_f32 v3, v4, v5
	global_store_dwordx2 v[210:211], v[2:3], off offset:1232
	v_mov_b64_e32 v[2:3], v[168:169]
	v_mov_b64_e32 v[4:5], v[170:171]
	v_mov_b32_e32 v6, v20
	v_mov_b32_e32 v7, v22
	v_mov_b32_e32 v20, v23
	v_pk_mul_f32 v[6:7], v[6:7], v[0:1] op_sel_hi:[1,0]
	v_pk_mul_f32 v[8:9], v[20:21], v[0:1] op_sel_hi:[1,0]
	v_pk_mul_f32 v[2:3], v[6:7], v[2:3]
	v_pk_mul_f32 v[4:5], v[8:9], v[4:5]
	v_cvt_pk_bf16_f32 v2, v2, v3
	v_cvt_pk_bf16_f32 v3, v4, v5
	global_store_dwordx2 v[210:211], v[2:3], off offset:1248
	v_mov_b64_e32 v[2:3], v[172:173]
	v_mov_b64_e32 v[4:5], v[174:175]
	v_mov_b32_e32 v6, v16
	v_mov_b32_e32 v7, v18
	v_mov_b32_e32 v16, v19
	v_pk_mul_f32 v[6:7], v[6:7], v[0:1] op_sel_hi:[1,0]
	v_pk_mul_f32 v[0:1], v[16:17], v[0:1] op_sel_hi:[1,0]
	v_pk_mul_f32 v[2:3], v[6:7], v[2:3]
	v_pk_mul_f32 v[0:1], v[0:1], v[4:5]
	v_cvt_pk_bf16_f32 v2, v2, v3
	v_cvt_pk_bf16_f32 v3, v0, v1
	global_store_dwordx2 v[210:211], v[2:3], off offset:1264
	s_cbranch_scc1 .LBB0_613
